# O1->da grid barrier replaced by a 32-workgroup shard (batch) barrier on top of the three panel barriers; stress-tested with forced skew
# baseline (speedup 1.0000x reference)
.LBB0_226:
	s_getreg_b32 s0, hwreg(HW_REG_XCC_ID, 0, 4)
	s_and_b32 s9, s0, 15
	s_waitcnt vmcnt(0)
	s_waitcnt vmcnt(0)
	s_barrier
	s_and_saveexec_b64 s[0:1], s[52:53]
	v_readlane_b32 s24, v255, 22
	s_cbranch_execz .LBB0_278
	v_readlane_b32 s98, v253, 2
	v_readlane_b32 s99, v253, 3
	s_nop 0
	s_add_u32 s98, s98, 0x7c000
	s_addc_u32 s99, s99, 0
	s_and_b32 vcc_hi, s2, 7
	s_sub_u32 vcc_lo, 7, vcc_hi
	s_add_u32 vcc_lo, vcc_lo, s3
	s_lshr_b32 vcc_lo, vcc_lo, 3
	s_lshl_b32 vcc_hi, vcc_hi, 8
	s_add_u32 vcc_hi, vcc_hi, 0x8000
	s_cmp_lt_u32 s101, 6
	s_cselect_b32 m0, 0, 0x800
	s_add_u32 vcc_hi, vcc_hi, m0
	v_mov_b32_e32 v3, vcc_hi
	v_mov_b32_e32 v4, 1
	s_mov_b32 vcc_hi, vcc_lo
	s_waitcnt vmcnt(0) lgkmcnt(0)
	global_atomic_add v5, v3, v4, s[98:99] sc0
	s_waitcnt vmcnt(0)
	v_readfirstlane_b32 vcc_lo, v5
	s_add_i32 vcc_lo, vcc_lo, 1
	s_cmp_ge_u32 vcc_lo, vcc_hi
	s_cbranch_scc1 .Lb3_ok_1
